# per-tile GEMM prologue: accumulators zeroed once with packed 64-bit moves (64 instead of 2x128 VALU per tile)
# speedup vs baseline: 1.0136x; 1.0067x over previous
; template <class Epi>
; __device__ __forceinline__ void gemm_phase(LAS unsigned char* lds, const Gemm g, const StaticOrder& S, const Epi& E) {
;     ...
;         const bool has_next = S.next(ui + 1, nxt);
;         const char* nA = has_next ? (const char*)g.A + (size_t)nxt.pm * tstep : cA; const char* nB = has_next ? (const char*)g.Bt + (size_t)nxt.pn * tstep : cB;
;         for (int t = 0; t < nt; t += 2) {
;             const bool last = (t == nt - 2);
;             const char* a1 = cA + (size_t)(t + 1) * kstep;
;             const char* a2 = last ? nA : cA + (size_t)(t + 2) * kstep; const char* b2 = last ? nB : cB + (size_t)(t + 2) * kstep;
;     ...
; #pragma unroll
;         for (int a = 0; a < 2; ++a)
; #pragma unroll
;             for (int b = 0; b < 2; ++b)
; #pragma unroll
;                 for (int m = 0; m < 4; ++m)
; #pragma unroll
;                     for (int n = 0; n < 2; ++n) acc[a][b][m][n] = (f32x4){0.f, 0.f, 0.f, 0.f};
;         cur = nxt; cA = nA; cB = nB; ++ui;
.LBB0_45:
	v_mov_b32_e32 v2, 0
	s_andn2_b64 vcc, exec, s[10:11]
	v_mov_b32_e32 v3, 0
	v_pk_mov_b32 v[4:5], v[2:3], v[2:3]
	v_pk_mov_b32 v[6:7], v[2:3], v[2:3]
	v_pk_mov_b32 v[8:9], v[2:3], v[2:3]
	v_pk_mov_b32 v[10:11], v[2:3], v[2:3]
	v_pk_mov_b32 v[12:13], v[2:3], v[2:3]
	v_pk_mov_b32 v[14:15], v[2:3], v[2:3]
	v_pk_mov_b32 v[16:17], v[2:3], v[2:3]
	v_pk_mov_b32 v[18:19], v[2:3], v[2:3]
	v_pk_mov_b32 v[20:21], v[2:3], v[2:3]
	v_pk_mov_b32 v[22:23], v[2:3], v[2:3]
	v_pk_mov_b32 v[24:25], v[2:3], v[2:3]
	v_pk_mov_b32 v[26:27], v[2:3], v[2:3]
	v_pk_mov_b32 v[28:29], v[2:3], v[2:3]
	v_pk_mov_b32 v[30:31], v[2:3], v[2:3]
	v_pk_mov_b32 v[32:33], v[2:3], v[2:3]
	v_pk_mov_b32 v[34:35], v[2:3], v[2:3]
	v_pk_mov_b32 v[36:37], v[2:3], v[2:3]
	v_pk_mov_b32 v[38:39], v[2:3], v[2:3]
	v_pk_mov_b32 v[40:41], v[2:3], v[2:3]
	v_pk_mov_b32 v[42:43], v[2:3], v[2:3]
	v_pk_mov_b32 v[44:45], v[2:3], v[2:3]
	v_pk_mov_b32 v[46:47], v[2:3], v[2:3]
	v_pk_mov_b32 v[48:49], v[2:3], v[2:3]
	v_pk_mov_b32 v[50:51], v[2:3], v[2:3]
	v_pk_mov_b32 v[52:53], v[2:3], v[2:3]
	v_pk_mov_b32 v[54:55], v[2:3], v[2:3]
	v_pk_mov_b32 v[56:57], v[2:3], v[2:3]
	v_pk_mov_b32 v[58:59], v[2:3], v[2:3]
	v_pk_mov_b32 v[60:61], v[2:3], v[2:3]
	v_pk_mov_b32 v[62:63], v[2:3], v[2:3]
	v_pk_mov_b32 v[64:65], v[2:3], v[2:3]
	v_pk_mov_b32 v[66:67], v[2:3], v[2:3]
	v_pk_mov_b32 v[68:69], v[2:3], v[2:3]
	v_pk_mov_b32 v[70:71], v[2:3], v[2:3]
	v_pk_mov_b32 v[72:73], v[2:3], v[2:3]
	v_pk_mov_b32 v[74:75], v[2:3], v[2:3]
	v_pk_mov_b32 v[76:77], v[2:3], v[2:3]
	v_pk_mov_b32 v[78:79], v[2:3], v[2:3]
	v_pk_mov_b32 v[80:81], v[2:3], v[2:3]
	v_pk_mov_b32 v[82:83], v[2:3], v[2:3]
	v_pk_mov_b32 v[84:85], v[2:3], v[2:3]
	v_pk_mov_b32 v[86:87], v[2:3], v[2:3]
	v_pk_mov_b32 v[88:89], v[2:3], v[2:3]
	v_pk_mov_b32 v[90:91], v[2:3], v[2:3]
	v_pk_mov_b32 v[92:93], v[2:3], v[2:3]
	v_pk_mov_b32 v[94:95], v[2:3], v[2:3]
	v_pk_mov_b32 v[96:97], v[2:3], v[2:3]
	v_pk_mov_b32 v[98:99], v[2:3], v[2:3]
	v_pk_mov_b32 v[100:101], v[2:3], v[2:3]
	v_pk_mov_b32 v[102:103], v[2:3], v[2:3]
	v_pk_mov_b32 v[104:105], v[2:3], v[2:3]
	v_pk_mov_b32 v[106:107], v[2:3], v[2:3]
	v_pk_mov_b32 v[108:109], v[2:3], v[2:3]
	v_pk_mov_b32 v[110:111], v[2:3], v[2:3]
	v_pk_mov_b32 v[112:113], v[2:3], v[2:3]
	v_pk_mov_b32 v[114:115], v[2:3], v[2:3]
	v_pk_mov_b32 v[116:117], v[2:3], v[2:3]
	v_pk_mov_b32 v[118:119], v[2:3], v[2:3]
	v_pk_mov_b32 v[120:121], v[2:3], v[2:3]
	v_pk_mov_b32 v[122:123], v[2:3], v[2:3]
	v_pk_mov_b32 v[124:125], v[2:3], v[2:3]
	v_pk_mov_b32 v[126:127], v[2:3], v[2:3]
	v_pk_mov_b32 v[128:129], v[2:3], v[2:3]
	s_cbranch_vccnz .LBB0_48
	s_add_u32 s16, s16, 0x80
	s_addc_u32 s17, s17, 0
	s_add_u32 s42, s18, 0x100
	s_addc_u32 s43, s19, 0
	s_mov_b32 s18, 0

; template <class Epi>
; __device__ __forceinline__ void gemm_phase(LAS unsigned char* lds, const Gemm g, const StaticOrder& S, const Epi& E) {
;     ...
;         const bool has_next = S.next(ui + 1, nxt);
;         const char* nA = has_next ? (const char*)g.A + (size_t)nxt.pm * tstep : cA; const char* nB = has_next ? (const char*)g.Bt + (size_t)nxt.pn * tstep : cB;
;         for (int t = 0; t < nt; t += 2) {
;             const bool last = (t == nt - 2);
;             const char* a1 = cA + (size_t)(t + 1) * kstep;
;             const char* a2 = last ? nA : cA + (size_t)(t + 2) * kstep; const char* b2 = last ? nB : cB + (size_t)(t + 2) * kstep;
;     ...
; #pragma unroll
;         for (int a = 0; a < 2; ++a)
; #pragma unroll
;             for (int b = 0; b < 2; ++b)
; #pragma unroll
;                 for (int m = 0; m < 4; ++m)
; #pragma unroll
;                     for (int n = 0; n < 2; ++n) acc[a][b][m][n] = (f32x4){0.f, 0.f, 0.f, 0.f};
;         cur = nxt; cA = nA; cB = nB; ++ui;
.LBB0_611:
	v_mov_b32_e32 v2, 0
	s_andn2_b64 vcc, exec, s[50:51]
	v_mov_b32_e32 v3, 0
	v_pk_mov_b32 v[4:5], v[2:3], v[2:3]
	v_pk_mov_b32 v[6:7], v[2:3], v[2:3]
	v_pk_mov_b32 v[8:9], v[2:3], v[2:3]
	v_pk_mov_b32 v[10:11], v[2:3], v[2:3]
	v_pk_mov_b32 v[12:13], v[2:3], v[2:3]
	v_pk_mov_b32 v[14:15], v[2:3], v[2:3]
	v_pk_mov_b32 v[16:17], v[2:3], v[2:3]
	v_pk_mov_b32 v[18:19], v[2:3], v[2:3]
	v_pk_mov_b32 v[20:21], v[2:3], v[2:3]
	v_pk_mov_b32 v[22:23], v[2:3], v[2:3]
	v_pk_mov_b32 v[24:25], v[2:3], v[2:3]
	v_pk_mov_b32 v[26:27], v[2:3], v[2:3]
	v_pk_mov_b32 v[28:29], v[2:3], v[2:3]
	v_pk_mov_b32 v[30:31], v[2:3], v[2:3]
	v_pk_mov_b32 v[32:33], v[2:3], v[2:3]
	v_pk_mov_b32 v[34:35], v[2:3], v[2:3]
	v_pk_mov_b32 v[36:37], v[2:3], v[2:3]
	v_pk_mov_b32 v[38:39], v[2:3], v[2:3]
	v_pk_mov_b32 v[40:41], v[2:3], v[2:3]
	v_pk_mov_b32 v[42:43], v[2:3], v[2:3]
	v_pk_mov_b32 v[44:45], v[2:3], v[2:3]
	v_pk_mov_b32 v[46:47], v[2:3], v[2:3]
	v_pk_mov_b32 v[48:49], v[2:3], v[2:3]
	v_pk_mov_b32 v[50:51], v[2:3], v[2:3]
	v_pk_mov_b32 v[52:53], v[2:3], v[2:3]
	v_pk_mov_b32 v[54:55], v[2:3], v[2:3]
	v_pk_mov_b32 v[56:57], v[2:3], v[2:3]
	v_pk_mov_b32 v[58:59], v[2:3], v[2:3]
	v_pk_mov_b32 v[60:61], v[2:3], v[2:3]
	v_pk_mov_b32 v[62:63], v[2:3], v[2:3]
	v_pk_mov_b32 v[64:65], v[2:3], v[2:3]
	v_pk_mov_b32 v[66:67], v[2:3], v[2:3]
	v_pk_mov_b32 v[68:69], v[2:3], v[2:3]
	v_pk_mov_b32 v[70:71], v[2:3], v[2:3]
	v_pk_mov_b32 v[72:73], v[2:3], v[2:3]
	v_pk_mov_b32 v[74:75], v[2:3], v[2:3]
	v_pk_mov_b32 v[76:77], v[2:3], v[2:3]
	v_pk_mov_b32 v[78:79], v[2:3], v[2:3]
	v_pk_mov_b32 v[80:81], v[2:3], v[2:3]
	v_pk_mov_b32 v[82:83], v[2:3], v[2:3]
	v_pk_mov_b32 v[84:85], v[2:3], v[2:3]
	v_pk_mov_b32 v[86:87], v[2:3], v[2:3]
	v_pk_mov_b32 v[88:89], v[2:3], v[2:3]
	v_pk_mov_b32 v[90:91], v[2:3], v[2:3]
	v_pk_mov_b32 v[92:93], v[2:3], v[2:3]
	v_pk_mov_b32 v[94:95], v[2:3], v[2:3]
	v_pk_mov_b32 v[96:97], v[2:3], v[2:3]
	v_pk_mov_b32 v[98:99], v[2:3], v[2:3]
	v_pk_mov_b32 v[100:101], v[2:3], v[2:3]
	v_pk_mov_b32 v[102:103], v[2:3], v[2:3]
	v_pk_mov_b32 v[104:105], v[2:3], v[2:3]
	v_pk_mov_b32 v[106:107], v[2:3], v[2:3]
	s_waitcnt vmcnt(0)
	v_pk_mov_b32 v[108:109], v[2:3], v[2:3]
	v_pk_mov_b32 v[110:111], v[2:3], v[2:3]
	v_pk_mov_b32 v[112:113], v[2:3], v[2:3]
	v_pk_mov_b32 v[114:115], v[2:3], v[2:3]
	v_pk_mov_b32 v[116:117], v[2:3], v[2:3]
	v_pk_mov_b32 v[118:119], v[2:3], v[2:3]
	v_pk_mov_b32 v[120:121], v[2:3], v[2:3]
	v_pk_mov_b32 v[122:123], v[2:3], v[2:3]
	v_pk_mov_b32 v[124:125], v[2:3], v[2:3]
	v_pk_mov_b32 v[126:127], v[2:3], v[2:3]
	v_pk_mov_b32 v[128:129], v[2:3], v[2:3]
	s_cbranch_vccnz .LBB0_614
	s_add_u32 s2, s2, 0x80
	s_addc_u32 s3, s3, 0
	s_add_u32 s26, s4, 0x100
	s_addc_u32 s28, s5, 0
	s_mov_b32 s4, 0

; template <class Epi>
; __device__ __forceinline__ void gemm_phase(LAS unsigned char* lds, const Gemm g, const StaticOrder& S, const Epi& E) {
;     ...
;         const bool has_next = S.next(ui + 1, nxt);
;         const char* nA = has_next ? (const char*)g.A + (size_t)nxt.pm * tstep : cA; const char* nB = has_next ? (const char*)g.Bt + (size_t)nxt.pn * tstep : cB;
;         for (int t = 0; t < nt; t += 2) {
;             const bool last = (t == nt - 2);
;             const char* a1 = cA + (size_t)(t + 1) * kstep;
;             const char* a2 = last ? nA : cA + (size_t)(t + 2) * kstep; const char* b2 = last ? nB : cB + (size_t)(t + 2) * kstep;
;     ...
; #pragma unroll
;         for (int a = 0; a < 2; ++a)
; #pragma unroll
;             for (int b = 0; b < 2; ++b)
; #pragma unroll
;                 for (int m = 0; m < 4; ++m)
; #pragma unroll
;                     for (int n = 0; n < 2; ++n) acc[a][b][m][n] = (f32x4){0.f, 0.f, 0.f, 0.f};
;         cur = nxt; cA = nA; cB = nB; ++ui;
.LBB0_749:
	v_mov_b32_e32 v2, 0
	s_andn2_b64 vcc, exec, s[8:9]
	v_mov_b32_e32 v3, 0
	v_pk_mov_b32 v[4:5], v[2:3], v[2:3]
	v_pk_mov_b32 v[6:7], v[2:3], v[2:3]
	v_pk_mov_b32 v[8:9], v[2:3], v[2:3]
	v_pk_mov_b32 v[10:11], v[2:3], v[2:3]
	v_pk_mov_b32 v[12:13], v[2:3], v[2:3]
	v_pk_mov_b32 v[14:15], v[2:3], v[2:3]
	v_pk_mov_b32 v[16:17], v[2:3], v[2:3]
	v_pk_mov_b32 v[18:19], v[2:3], v[2:3]
	v_pk_mov_b32 v[20:21], v[2:3], v[2:3]
	v_pk_mov_b32 v[22:23], v[2:3], v[2:3]
	v_pk_mov_b32 v[24:25], v[2:3], v[2:3]
	v_pk_mov_b32 v[26:27], v[2:3], v[2:3]
	v_pk_mov_b32 v[28:29], v[2:3], v[2:3]
	v_pk_mov_b32 v[30:31], v[2:3], v[2:3]
	v_pk_mov_b32 v[32:33], v[2:3], v[2:3]
	v_pk_mov_b32 v[34:35], v[2:3], v[2:3]
	v_pk_mov_b32 v[36:37], v[2:3], v[2:3]
	v_pk_mov_b32 v[38:39], v[2:3], v[2:3]
	v_pk_mov_b32 v[40:41], v[2:3], v[2:3]
	v_pk_mov_b32 v[42:43], v[2:3], v[2:3]
	v_pk_mov_b32 v[44:45], v[2:3], v[2:3]
	v_pk_mov_b32 v[46:47], v[2:3], v[2:3]
	v_pk_mov_b32 v[48:49], v[2:3], v[2:3]
	v_pk_mov_b32 v[50:51], v[2:3], v[2:3]
	v_pk_mov_b32 v[52:53], v[2:3], v[2:3]
	v_pk_mov_b32 v[54:55], v[2:3], v[2:3]
	v_pk_mov_b32 v[56:57], v[2:3], v[2:3]
	v_pk_mov_b32 v[58:59], v[2:3], v[2:3]
	v_pk_mov_b32 v[60:61], v[2:3], v[2:3]
	v_pk_mov_b32 v[62:63], v[2:3], v[2:3]
	v_pk_mov_b32 v[64:65], v[2:3], v[2:3]
	v_pk_mov_b32 v[66:67], v[2:3], v[2:3]
	v_pk_mov_b32 v[68:69], v[2:3], v[2:3]
	v_pk_mov_b32 v[70:71], v[2:3], v[2:3]
	v_pk_mov_b32 v[72:73], v[2:3], v[2:3]
	v_pk_mov_b32 v[74:75], v[2:3], v[2:3]
	v_pk_mov_b32 v[76:77], v[2:3], v[2:3]
	v_pk_mov_b32 v[78:79], v[2:3], v[2:3]
	v_pk_mov_b32 v[80:81], v[2:3], v[2:3]
	v_pk_mov_b32 v[82:83], v[2:3], v[2:3]
	v_pk_mov_b32 v[84:85], v[2:3], v[2:3]
	v_pk_mov_b32 v[86:87], v[2:3], v[2:3]
	v_pk_mov_b32 v[88:89], v[2:3], v[2:3]
	v_pk_mov_b32 v[90:91], v[2:3], v[2:3]
	v_pk_mov_b32 v[92:93], v[2:3], v[2:3]
	v_pk_mov_b32 v[94:95], v[2:3], v[2:3]
	v_pk_mov_b32 v[96:97], v[2:3], v[2:3]
	v_pk_mov_b32 v[98:99], v[2:3], v[2:3]
	v_pk_mov_b32 v[100:101], v[2:3], v[2:3]
	v_pk_mov_b32 v[102:103], v[2:3], v[2:3]
	v_pk_mov_b32 v[104:105], v[2:3], v[2:3]
	v_pk_mov_b32 v[106:107], v[2:3], v[2:3]
	v_pk_mov_b32 v[108:109], v[2:3], v[2:3]
	v_pk_mov_b32 v[110:111], v[2:3], v[2:3]
	v_pk_mov_b32 v[112:113], v[2:3], v[2:3]
	v_pk_mov_b32 v[114:115], v[2:3], v[2:3]
	v_pk_mov_b32 v[116:117], v[2:3], v[2:3]
	v_pk_mov_b32 v[118:119], v[2:3], v[2:3]
	v_pk_mov_b32 v[120:121], v[2:3], v[2:3]
	v_pk_mov_b32 v[122:123], v[2:3], v[2:3]
	v_pk_mov_b32 v[124:125], v[2:3], v[2:3]
	v_pk_mov_b32 v[126:127], v[2:3], v[2:3]
	v_pk_mov_b32 v[128:129], v[2:3], v[2:3]
	s_cbranch_vccnz .LBB0_738
	s_add_u32 s14, s14, 0x80
	s_addc_u32 s15, s15, 0
	s_add_u32 s42, s16, 0x100
	s_addc_u32 s43, s17, 0
	s_mov_b32 s16, 0

; template <class Epi>
; __device__ __forceinline__ void gemm_phase(LAS unsigned char* lds, const Gemm g, const StaticOrder& S, const Epi& E) {
;     ...
;         const bool has_next = S.next(ui + 1, nxt);
;         const char* nA = has_next ? (const char*)g.A + (size_t)nxt.pm * tstep : cA; const char* nB = has_next ? (const char*)g.Bt + (size_t)nxt.pn * tstep : cB;
;         for (int t = 0; t < nt; t += 2) {
;             const bool last = (t == nt - 2);
;             const char* a1 = cA + (size_t)(t + 1) * kstep;
;             const char* a2 = last ? nA : cA + (size_t)(t + 2) * kstep; const char* b2 = last ? nB : cB + (size_t)(t + 2) * kstep;
;     ...
; #pragma unroll
;         for (int a = 0; a < 2; ++a)
; #pragma unroll
;             for (int b = 0; b < 2; ++b)
; #pragma unroll
;                 for (int m = 0; m < 4; ++m)
; #pragma unroll
;                     for (int n = 0; n < 2; ++n) acc[a][b][m][n] = (f32x4){0.f, 0.f, 0.f, 0.f};
;         cur = nxt; cA = nA; cB = nB; ++ui;
.LBB0_777:
	v_mov_b32_e32 v2, 0
	s_andn2_b64 vcc, exec, s[46:47]
	v_mov_b32_e32 v3, 0
	v_pk_mov_b32 v[4:5], v[2:3], v[2:3]
	v_pk_mov_b32 v[6:7], v[2:3], v[2:3]
	v_pk_mov_b32 v[8:9], v[2:3], v[2:3]
	v_pk_mov_b32 v[10:11], v[2:3], v[2:3]
	v_pk_mov_b32 v[12:13], v[2:3], v[2:3]
	v_pk_mov_b32 v[14:15], v[2:3], v[2:3]
	v_pk_mov_b32 v[16:17], v[2:3], v[2:3]
	v_pk_mov_b32 v[18:19], v[2:3], v[2:3]
	v_pk_mov_b32 v[20:21], v[2:3], v[2:3]
	v_pk_mov_b32 v[22:23], v[2:3], v[2:3]
	v_pk_mov_b32 v[24:25], v[2:3], v[2:3]
	v_pk_mov_b32 v[26:27], v[2:3], v[2:3]
	v_pk_mov_b32 v[28:29], v[2:3], v[2:3]
	v_pk_mov_b32 v[30:31], v[2:3], v[2:3]
	v_pk_mov_b32 v[32:33], v[2:3], v[2:3]
	v_pk_mov_b32 v[34:35], v[2:3], v[2:3]
	v_pk_mov_b32 v[36:37], v[2:3], v[2:3]
	v_pk_mov_b32 v[38:39], v[2:3], v[2:3]
	v_pk_mov_b32 v[40:41], v[2:3], v[2:3]
	v_pk_mov_b32 v[42:43], v[2:3], v[2:3]
	v_pk_mov_b32 v[44:45], v[2:3], v[2:3]
	v_pk_mov_b32 v[46:47], v[2:3], v[2:3]
	v_pk_mov_b32 v[48:49], v[2:3], v[2:3]
	v_pk_mov_b32 v[50:51], v[2:3], v[2:3]
	v_pk_mov_b32 v[52:53], v[2:3], v[2:3]
	v_pk_mov_b32 v[54:55], v[2:3], v[2:3]
	v_pk_mov_b32 v[56:57], v[2:3], v[2:3]
	v_pk_mov_b32 v[58:59], v[2:3], v[2:3]
	v_pk_mov_b32 v[60:61], v[2:3], v[2:3]
	v_pk_mov_b32 v[62:63], v[2:3], v[2:3]
	v_pk_mov_b32 v[64:65], v[2:3], v[2:3]
	v_pk_mov_b32 v[66:67], v[2:3], v[2:3]
	v_pk_mov_b32 v[68:69], v[2:3], v[2:3]
	v_pk_mov_b32 v[70:71], v[2:3], v[2:3]
	v_pk_mov_b32 v[72:73], v[2:3], v[2:3]
	v_pk_mov_b32 v[74:75], v[2:3], v[2:3]
	v_pk_mov_b32 v[76:77], v[2:3], v[2:3]
	v_pk_mov_b32 v[78:79], v[2:3], v[2:3]
	v_pk_mov_b32 v[80:81], v[2:3], v[2:3]
	v_pk_mov_b32 v[82:83], v[2:3], v[2:3]
	v_pk_mov_b32 v[84:85], v[2:3], v[2:3]
	v_pk_mov_b32 v[86:87], v[2:3], v[2:3]
	v_pk_mov_b32 v[88:89], v[2:3], v[2:3]
	v_pk_mov_b32 v[90:91], v[2:3], v[2:3]
	v_pk_mov_b32 v[92:93], v[2:3], v[2:3]
	v_pk_mov_b32 v[94:95], v[2:3], v[2:3]
	v_pk_mov_b32 v[96:97], v[2:3], v[2:3]
	v_pk_mov_b32 v[98:99], v[2:3], v[2:3]
	v_pk_mov_b32 v[100:101], v[2:3], v[2:3]
	v_pk_mov_b32 v[102:103], v[2:3], v[2:3]
	v_pk_mov_b32 v[104:105], v[2:3], v[2:3]
	v_pk_mov_b32 v[106:107], v[2:3], v[2:3]
	v_pk_mov_b32 v[108:109], v[2:3], v[2:3]
	v_pk_mov_b32 v[110:111], v[2:3], v[2:3]
	v_pk_mov_b32 v[112:113], v[2:3], v[2:3]
	v_pk_mov_b32 v[114:115], v[2:3], v[2:3]
	v_pk_mov_b32 v[116:117], v[2:3], v[2:3]
	v_pk_mov_b32 v[118:119], v[2:3], v[2:3]
	v_pk_mov_b32 v[120:121], v[2:3], v[2:3]
	v_pk_mov_b32 v[122:123], v[2:3], v[2:3]
	v_pk_mov_b32 v[124:125], v[2:3], v[2:3]
	v_pk_mov_b32 v[126:127], v[2:3], v[2:3]
	v_pk_mov_b32 v[128:129], v[2:3], v[2:3]
	s_cbranch_vccnz .LBB0_781
	s_add_u32 s2, s2, 0x80
	s_addc_u32 s3, s3, 0
	s_add_u32 s28, s4, 0x100
	s_addc_u32 s42, s5, 0
	s_mov_b32 s4, 0

; template <class Epi>
; __device__ __forceinline__ void gemm_phase(LAS unsigned char* lds, const Gemm g, const StaticOrder& S, const Epi& E) {
;     ...
;         const bool has_next = S.next(ui + 1, nxt);
;         const char* nA = has_next ? (const char*)g.A + (size_t)nxt.pm * tstep : cA; const char* nB = has_next ? (const char*)g.Bt + (size_t)nxt.pn * tstep : cB;
;         for (int t = 0; t < nt; t += 2) {
;             const bool last = (t == nt - 2);
;             const char* a1 = cA + (size_t)(t + 1) * kstep;
;             const char* a2 = last ? nA : cA + (size_t)(t + 2) * kstep; const char* b2 = last ? nB : cB + (size_t)(t + 2) * kstep;
;     ...
; #pragma unroll
;         for (int a = 0; a < 2; ++a)
; #pragma unroll
;             for (int b = 0; b < 2; ++b)
; #pragma unroll
;                 for (int m = 0; m < 4; ++m)
; #pragma unroll
;                     for (int n = 0; n < 2; ++n) acc[a][b][m][n] = (f32x4){0.f, 0.f, 0.f, 0.f};
;         cur = nxt; cA = nA; cB = nB; ++ui;
.LBB0_847:
	v_mov_b32_e32 v2, 0
	s_andn2_b64 vcc, exec, s[10:11]
	v_mov_b32_e32 v3, 0
	v_pk_mov_b32 v[4:5], v[2:3], v[2:3]
	v_pk_mov_b32 v[6:7], v[2:3], v[2:3]
	v_pk_mov_b32 v[8:9], v[2:3], v[2:3]
	v_pk_mov_b32 v[10:11], v[2:3], v[2:3]
	v_pk_mov_b32 v[12:13], v[2:3], v[2:3]
	v_pk_mov_b32 v[14:15], v[2:3], v[2:3]
	v_pk_mov_b32 v[16:17], v[2:3], v[2:3]
	v_pk_mov_b32 v[18:19], v[2:3], v[2:3]
	v_pk_mov_b32 v[20:21], v[2:3], v[2:3]
	v_pk_mov_b32 v[22:23], v[2:3], v[2:3]
	v_pk_mov_b32 v[24:25], v[2:3], v[2:3]
	v_pk_mov_b32 v[26:27], v[2:3], v[2:3]
	v_pk_mov_b32 v[28:29], v[2:3], v[2:3]
	v_pk_mov_b32 v[30:31], v[2:3], v[2:3]
	v_pk_mov_b32 v[32:33], v[2:3], v[2:3]
	v_pk_mov_b32 v[34:35], v[2:3], v[2:3]
	v_pk_mov_b32 v[36:37], v[2:3], v[2:3]
	v_pk_mov_b32 v[38:39], v[2:3], v[2:3]
	v_pk_mov_b32 v[40:41], v[2:3], v[2:3]
	v_pk_mov_b32 v[42:43], v[2:3], v[2:3]
	v_pk_mov_b32 v[44:45], v[2:3], v[2:3]
	v_pk_mov_b32 v[46:47], v[2:3], v[2:3]
	v_pk_mov_b32 v[48:49], v[2:3], v[2:3]
	v_pk_mov_b32 v[50:51], v[2:3], v[2:3]
	v_pk_mov_b32 v[52:53], v[2:3], v[2:3]
	v_pk_mov_b32 v[54:55], v[2:3], v[2:3]
	v_pk_mov_b32 v[56:57], v[2:3], v[2:3]
	v_pk_mov_b32 v[58:59], v[2:3], v[2:3]
	v_pk_mov_b32 v[60:61], v[2:3], v[2:3]
	v_pk_mov_b32 v[62:63], v[2:3], v[2:3]
	v_pk_mov_b32 v[64:65], v[2:3], v[2:3]
	v_pk_mov_b32 v[66:67], v[2:3], v[2:3]
	v_pk_mov_b32 v[68:69], v[2:3], v[2:3]
	v_pk_mov_b32 v[70:71], v[2:3], v[2:3]
	v_pk_mov_b32 v[72:73], v[2:3], v[2:3]
	v_pk_mov_b32 v[74:75], v[2:3], v[2:3]
	v_pk_mov_b32 v[76:77], v[2:3], v[2:3]
	v_pk_mov_b32 v[78:79], v[2:3], v[2:3]
	v_pk_mov_b32 v[80:81], v[2:3], v[2:3]
	v_pk_mov_b32 v[82:83], v[2:3], v[2:3]
	v_pk_mov_b32 v[84:85], v[2:3], v[2:3]
	v_pk_mov_b32 v[86:87], v[2:3], v[2:3]
	v_pk_mov_b32 v[88:89], v[2:3], v[2:3]
	v_pk_mov_b32 v[90:91], v[2:3], v[2:3]
	v_pk_mov_b32 v[92:93], v[2:3], v[2:3]
	v_pk_mov_b32 v[94:95], v[2:3], v[2:3]
	v_pk_mov_b32 v[96:97], v[2:3], v[2:3]
	v_pk_mov_b32 v[98:99], v[2:3], v[2:3]
	v_pk_mov_b32 v[100:101], v[2:3], v[2:3]
	v_pk_mov_b32 v[102:103], v[2:3], v[2:3]
	v_pk_mov_b32 v[104:105], v[2:3], v[2:3]
	v_pk_mov_b32 v[106:107], v[2:3], v[2:3]
	v_pk_mov_b32 v[108:109], v[2:3], v[2:3]
	v_pk_mov_b32 v[110:111], v[2:3], v[2:3]
	v_pk_mov_b32 v[112:113], v[2:3], v[2:3]
	v_pk_mov_b32 v[114:115], v[2:3], v[2:3]
	s_waitcnt vmcnt(0)
	v_pk_mov_b32 v[116:117], v[2:3], v[2:3]
	v_pk_mov_b32 v[118:119], v[2:3], v[2:3]
	v_pk_mov_b32 v[120:121], v[2:3], v[2:3]
	v_pk_mov_b32 v[122:123], v[2:3], v[2:3]
	v_pk_mov_b32 v[124:125], v[2:3], v[2:3]
	v_pk_mov_b32 v[126:127], v[2:3], v[2:3]
	v_pk_mov_b32 v[128:129], v[2:3], v[2:3]
	s_cbranch_vccnz .LBB0_851
	s_add_u32 s16, s16, 0x80
	s_addc_u32 s17, s17, 0
	s_add_u32 s42, s18, 0x100
	s_addc_u32 s43, s19, 0
	s_mov_b32 s18, 0

; template <class Epi>
; __device__ __forceinline__ void gemm_phase(LAS unsigned char* lds, const Gemm g, const StaticOrder& S, const Epi& E) {
;     ...
;         const bool has_next = S.next(ui + 1, nxt);
;         const char* nA = has_next ? (const char*)g.A + (size_t)nxt.pm * tstep : cA; const char* nB = has_next ? (const char*)g.Bt + (size_t)nxt.pn * tstep : cB;
;         for (int t = 0; t < nt; t += 2) {
;             const bool last = (t == nt - 2);
;             const char* a1 = cA + (size_t)(t + 1) * kstep;
;             const char* a2 = last ? nA : cA + (size_t)(t + 2) * kstep; const char* b2 = last ? nB : cB + (size_t)(t + 2) * kstep;
;     ...
; #pragma unroll
;         for (int a = 0; a < 2; ++a)
; #pragma unroll
;             for (int b = 0; b < 2; ++b)
; #pragma unroll
;                 for (int m = 0; m < 4; ++m)
; #pragma unroll
;                     for (int n = 0; n < 2; ++n) acc[a][b][m][n] = (f32x4){0.f, 0.f, 0.f, 0.f};
;         cur = nxt; cA = nA; cB = nB; ++ui;
.LBB0_886:
	v_readlane_b32 s42, v255, 27
	v_mov_b32_e32 v2, 0
	v_readlane_b32 s43, v255, 28
	s_andn2_b64 vcc, exec, s[42:43]
	v_mov_b32_e32 v3, 0
	v_pk_mov_b32 v[4:5], v[2:3], v[2:3]
	v_pk_mov_b32 v[6:7], v[2:3], v[2:3]
	v_pk_mov_b32 v[8:9], v[2:3], v[2:3]
	v_pk_mov_b32 v[10:11], v[2:3], v[2:3]
	v_pk_mov_b32 v[12:13], v[2:3], v[2:3]
	v_pk_mov_b32 v[14:15], v[2:3], v[2:3]
	v_pk_mov_b32 v[16:17], v[2:3], v[2:3]
	v_pk_mov_b32 v[18:19], v[2:3], v[2:3]
	v_pk_mov_b32 v[20:21], v[2:3], v[2:3]
	v_pk_mov_b32 v[22:23], v[2:3], v[2:3]
	v_pk_mov_b32 v[24:25], v[2:3], v[2:3]
	v_pk_mov_b32 v[26:27], v[2:3], v[2:3]
	v_pk_mov_b32 v[28:29], v[2:3], v[2:3]
	v_pk_mov_b32 v[30:31], v[2:3], v[2:3]
	v_pk_mov_b32 v[32:33], v[2:3], v[2:3]
	v_pk_mov_b32 v[34:35], v[2:3], v[2:3]
	v_pk_mov_b32 v[36:37], v[2:3], v[2:3]
	v_pk_mov_b32 v[38:39], v[2:3], v[2:3]
	v_pk_mov_b32 v[40:41], v[2:3], v[2:3]
	v_pk_mov_b32 v[42:43], v[2:3], v[2:3]
	v_pk_mov_b32 v[44:45], v[2:3], v[2:3]
	v_pk_mov_b32 v[46:47], v[2:3], v[2:3]
	v_pk_mov_b32 v[48:49], v[2:3], v[2:3]
	v_pk_mov_b32 v[50:51], v[2:3], v[2:3]
	v_pk_mov_b32 v[52:53], v[2:3], v[2:3]
	v_pk_mov_b32 v[54:55], v[2:3], v[2:3]
	v_pk_mov_b32 v[56:57], v[2:3], v[2:3]
	v_pk_mov_b32 v[58:59], v[2:3], v[2:3]
	s_waitcnt vmcnt(0)
	v_pk_mov_b32 v[60:61], v[2:3], v[2:3]
	v_pk_mov_b32 v[62:63], v[2:3], v[2:3]
	v_pk_mov_b32 v[64:65], v[2:3], v[2:3]
	v_pk_mov_b32 v[66:67], v[2:3], v[2:3]
	v_pk_mov_b32 v[68:69], v[2:3], v[2:3]
	v_pk_mov_b32 v[70:71], v[2:3], v[2:3]
	v_pk_mov_b32 v[72:73], v[2:3], v[2:3]
	v_pk_mov_b32 v[74:75], v[2:3], v[2:3]
	v_pk_mov_b32 v[76:77], v[2:3], v[2:3]
	v_pk_mov_b32 v[78:79], v[2:3], v[2:3]
	v_pk_mov_b32 v[80:81], v[2:3], v[2:3]
	v_pk_mov_b32 v[82:83], v[2:3], v[2:3]
	v_pk_mov_b32 v[84:85], v[2:3], v[2:3]
	v_pk_mov_b32 v[86:87], v[2:3], v[2:3]
	v_pk_mov_b32 v[88:89], v[2:3], v[2:3]
	v_pk_mov_b32 v[90:91], v[2:3], v[2:3]
	v_pk_mov_b32 v[92:93], v[2:3], v[2:3]
	v_pk_mov_b32 v[94:95], v[2:3], v[2:3]
	v_pk_mov_b32 v[96:97], v[2:3], v[2:3]
	v_pk_mov_b32 v[98:99], v[2:3], v[2:3]
	v_pk_mov_b32 v[100:101], v[2:3], v[2:3]
	v_pk_mov_b32 v[102:103], v[2:3], v[2:3]
	v_pk_mov_b32 v[104:105], v[2:3], v[2:3]
	v_pk_mov_b32 v[106:107], v[2:3], v[2:3]
	v_pk_mov_b32 v[108:109], v[2:3], v[2:3]
	v_pk_mov_b32 v[110:111], v[2:3], v[2:3]
	v_pk_mov_b32 v[112:113], v[2:3], v[2:3]
	v_pk_mov_b32 v[114:115], v[2:3], v[2:3]
	v_pk_mov_b32 v[116:117], v[2:3], v[2:3]
	v_pk_mov_b32 v[118:119], v[2:3], v[2:3]
	v_pk_mov_b32 v[120:121], v[2:3], v[2:3]
	v_pk_mov_b32 v[122:123], v[2:3], v[2:3]
	v_pk_mov_b32 v[124:125], v[2:3], v[2:3]
	v_pk_mov_b32 v[126:127], v[2:3], v[2:3]
	v_pk_mov_b32 v[128:129], v[2:3], v[2:3]
	s_cbranch_vccnz .LBB0_889
	s_add_u32 s50, s36, 0x100
	s_addc_u32 s51, s37, 0
	s_add_u32 s36, s46, 0x80
	s_addc_u32 s37, s47, 0
	s_mov_b32 s42, 0

; template <class Epi>
; __device__ __forceinline__ void gemm_phase(LAS unsigned char* lds, const Gemm g, const StaticOrder& S, const Epi& E) {
;     ...
;         const bool has_next = S.next(ui + 1, nxt);
;         const char* nA = has_next ? (const char*)g.A + (size_t)nxt.pm * tstep : cA; const char* nB = has_next ? (const char*)g.Bt + (size_t)nxt.pn * tstep : cB;
;         for (int t = 0; t < nt; t += 2) {
;             const bool last = (t == nt - 2);
;             const char* a1 = cA + (size_t)(t + 1) * kstep;
;             const char* a2 = last ? nA : cA + (size_t)(t + 2) * kstep; const char* b2 = last ? nB : cB + (size_t)(t + 2) * kstep;
;     ...
; #pragma unroll
;         for (int a = 0; a < 2; ++a)
; #pragma unroll
;             for (int b = 0; b < 2; ++b)
; #pragma unroll
;                 for (int m = 0; m < 4; ++m)
; #pragma unroll
;                     for (int n = 0; n < 2; ++n) acc[a][b][m][n] = (f32x4){0.f, 0.f, 0.f, 0.f};
;         cur = nxt; cA = nA; cB = nB; ++ui;
.LBB0_972:
	v_mov_b32_e32 v2, 0
	s_andn2_b64 vcc, exec, s[6:7]
	v_mov_b32_e32 v3, 0
	v_pk_mov_b32 v[4:5], v[2:3], v[2:3]
	v_pk_mov_b32 v[6:7], v[2:3], v[2:3]
	v_pk_mov_b32 v[8:9], v[2:3], v[2:3]
	v_pk_mov_b32 v[10:11], v[2:3], v[2:3]
	v_pk_mov_b32 v[12:13], v[2:3], v[2:3]
	v_pk_mov_b32 v[14:15], v[2:3], v[2:3]
	v_pk_mov_b32 v[16:17], v[2:3], v[2:3]
	v_pk_mov_b32 v[18:19], v[2:3], v[2:3]
	v_pk_mov_b32 v[20:21], v[2:3], v[2:3]
	v_pk_mov_b32 v[22:23], v[2:3], v[2:3]
	v_pk_mov_b32 v[24:25], v[2:3], v[2:3]
	v_pk_mov_b32 v[26:27], v[2:3], v[2:3]
	v_pk_mov_b32 v[28:29], v[2:3], v[2:3]
	v_pk_mov_b32 v[30:31], v[2:3], v[2:3]
	v_pk_mov_b32 v[32:33], v[2:3], v[2:3]
	v_pk_mov_b32 v[34:35], v[2:3], v[2:3]
	v_pk_mov_b32 v[36:37], v[2:3], v[2:3]
	v_pk_mov_b32 v[38:39], v[2:3], v[2:3]
	v_pk_mov_b32 v[40:41], v[2:3], v[2:3]
	v_pk_mov_b32 v[42:43], v[2:3], v[2:3]
	v_pk_mov_b32 v[44:45], v[2:3], v[2:3]
	v_pk_mov_b32 v[46:47], v[2:3], v[2:3]
	v_pk_mov_b32 v[48:49], v[2:3], v[2:3]
	v_pk_mov_b32 v[50:51], v[2:3], v[2:3]
	v_pk_mov_b32 v[52:53], v[2:3], v[2:3]
	v_pk_mov_b32 v[54:55], v[2:3], v[2:3]
	v_pk_mov_b32 v[56:57], v[2:3], v[2:3]
	v_pk_mov_b32 v[58:59], v[2:3], v[2:3]
	v_pk_mov_b32 v[60:61], v[2:3], v[2:3]
	v_pk_mov_b32 v[62:63], v[2:3], v[2:3]
	v_pk_mov_b32 v[64:65], v[2:3], v[2:3]
	v_pk_mov_b32 v[66:67], v[2:3], v[2:3]
	v_pk_mov_b32 v[68:69], v[2:3], v[2:3]
	v_pk_mov_b32 v[70:71], v[2:3], v[2:3]
	v_pk_mov_b32 v[72:73], v[2:3], v[2:3]
	v_pk_mov_b32 v[74:75], v[2:3], v[2:3]
	v_pk_mov_b32 v[76:77], v[2:3], v[2:3]
	v_pk_mov_b32 v[78:79], v[2:3], v[2:3]
	v_pk_mov_b32 v[80:81], v[2:3], v[2:3]
	v_pk_mov_b32 v[82:83], v[2:3], v[2:3]
	v_pk_mov_b32 v[84:85], v[2:3], v[2:3]
	v_pk_mov_b32 v[86:87], v[2:3], v[2:3]
	v_pk_mov_b32 v[88:89], v[2:3], v[2:3]
	v_pk_mov_b32 v[90:91], v[2:3], v[2:3]
	v_pk_mov_b32 v[92:93], v[2:3], v[2:3]
	v_pk_mov_b32 v[94:95], v[2:3], v[2:3]
	v_pk_mov_b32 v[96:97], v[2:3], v[2:3]
	v_pk_mov_b32 v[98:99], v[2:3], v[2:3]
	v_pk_mov_b32 v[100:101], v[2:3], v[2:3]
	v_pk_mov_b32 v[102:103], v[2:3], v[2:3]
	v_pk_mov_b32 v[104:105], v[2:3], v[2:3]
	v_pk_mov_b32 v[106:107], v[2:3], v[2:3]
	v_pk_mov_b32 v[108:109], v[2:3], v[2:3]
	v_pk_mov_b32 v[110:111], v[2:3], v[2:3]
	v_pk_mov_b32 v[112:113], v[2:3], v[2:3]
	v_pk_mov_b32 v[114:115], v[2:3], v[2:3]
	v_pk_mov_b32 v[116:117], v[2:3], v[2:3]
	v_pk_mov_b32 v[118:119], v[2:3], v[2:3]
	v_pk_mov_b32 v[120:121], v[2:3], v[2:3]
	v_pk_mov_b32 v[122:123], v[2:3], v[2:3]
	v_pk_mov_b32 v[124:125], v[2:3], v[2:3]
	v_pk_mov_b32 v[126:127], v[2:3], v[2:3]
	v_pk_mov_b32 v[128:129], v[2:3], v[2:3]
	s_cbranch_vccnz .LBB0_961
	s_add_u32 s12, s12, 0x80
	s_addc_u32 s13, s13, 0
	s_add_u32 s42, s14, 0x100
	s_addc_u32 s43, s15, 0
	s_mov_b32 s14, 0
